# GEMM phases P7/P9/P10: odd CUs start ~3.5/7 us later so that the CUs' epilogue memory bursts do not coincide
# speedup vs baseline: 1.0043x; 1.0043x over previous
.LBB0_1069:
	s_add_u32 s77, s74, 0x2000
	s_waitcnt vmcnt(0)
	v_lshrrev_b32_e32 v18, 1, v10
	s_addc_u32 s78, s75, 0
	v_and_b32_e32 v18, 24, v18
	s_lshl_b32 s0, s0, 5
	v_and_b32_e32 v17, 15, v10
	v_lshlrev_b32_e32 v19, 1, v18
	v_lshlrev_b32_e32 v10, 2, v10
	s_and_b32 s6, s0, 0x60
	s_add_i32 m0, s19, 0x18000
	v_lshl_add_u64 v[8:9], v[8:9], 0, s[56:57]
	v_lshl_or_b32 v188, s1, 6, v17
	v_lshl_or_b32 v17, v17, 6, v19
	s_lshl_b32 s1, s1, 13
	v_and_b32_e32 v10, 32, v10
	s_lshl_b32 s0, s6, 7
	s_waitcnt vmcnt(4)
	s_barrier
	global_load_lds_dwordx4 v[8:9], off
	v_lshl_add_u64 v[6:7], v[6:7], 0, s[56:57]
	s_add_i32 m0, s19, 0x1a000
	s_add_i32 s79, s19, 0x8000
	s_add_i32 s80, s19, 0xa000
	v_bitop3_b32 v189, v17, s0, v10 bitop3:0xde
	global_load_lds_dwordx4 v[6:7], off
	v_lshl_add_u64 v[4:5], v[4:5], 0, s[56:57]
	s_mov_b32 m0, s79
	s_add_u32 s0, s22, 0x40080
	v_bitop3_b32 v19, v17, s1, v10 bitop3:0xde
	global_load_lds_dwordx4 v[4:5], off
	v_lshl_add_u64 v[2:3], v[2:3], 0, s[56:57]
	s_mov_b32 m0, s80
	s_addc_u32 s1, s23, 0
	global_load_lds_dwordx4 v[2:3], off
	s_add_i32 m0, s19, 0x1c000
	v_lshl_add_u64 v[2:3], s[0:1], 0, v[0:1]
	global_load_lds_dwordx4 v[2:3], off
	v_lshl_add_u64 v[2:3], s[0:1], 0, v[170:171]
	s_add_i32 m0, s19, 0x1e000
	v_or_b32_e32 v190, s6, v18
	global_load_lds_dwordx4 v[2:3], off
	v_lshlrev_b32_e32 v2, 14, v11
	v_and_b32_e32 v2, 0xffff8000, v2
	v_lshl_add_u32 v2, v12, 11, v2
	v_and_b32_e32 v3, 1, v11
	v_lshl_or_b32 v2, v3, 6, v2
	v_lshl_add_u32 v172, v13, 1, v2
	v_lshlrev_b32_e32 v2, 14, v14
	v_and_b32_e32 v2, 0xffff8000, v2
	s_waitcnt vmcnt(6)
	v_lshl_add_u32 v2, v15, 11, v2
	v_and_b32_e32 v3, 1, v14
	v_lshl_or_b32 v2, v3, 6, v2
	v_mov_b32_e32 v173, v1
	v_lshl_add_u32 v174, v16, 1, v2
	v_mov_b32_e32 v175, v1
	s_mov_b32 s81, 0
	v_add_u32_e32 v191, 0, v19
	s_barrier
	s_bitcmp1_b32 s54, 0
	s_cbranch_scc0 .Lstg_p7
	s_sleep 127
	s_sleep 127
.Lstg_p7:
	s_branch .LBB0_1071
.LBB0_1070:
	s_and_b64 vcc, exec, s[0:1]
	s_mov_b32 s18, s6
	s_mov_b32 s16, s10
	s_mov_b64 s[22:23], s[14:15]
	s_mov_b64 s[20:21], s[12:13]
	s_cbranch_vccnz .LBB0_1084

.LBB0_1201:
	v_lshrrev_b32_e32 v18, 1, v6
	v_and_b32_e32 v18, 24, v18
	v_and_b32_e32 v9, 15, v6
	v_lshlrev_b32_e32 v19, 1, v18
	v_lshlrev_b32_e32 v6, 2, v6
	v_lshl_or_b32 v142, s0, 6, v9
	v_lshl_or_b32 v9, v9, 6, v19
	s_lshl_b32 s0, s0, 13
	v_and_b32_e32 v6, 32, v6
	v_lshl_add_u64 v[10:11], s[34:35], 0, v[0:1]
	v_mov_b32_e32 v135, v1
	v_bitop3_b32 v19, v9, s0, v6 bitop3:0xde
	s_lshl_b32 s0, s1, 5
	v_lshl_add_u64 v[12:13], s[34:35], 0, v[134:135]
	v_mov_b32_e32 v131, v1
	s_and_b32 s10, s0, 0x60
	s_add_i32 m0, s19, 0x18000
	v_lshl_add_u64 v[10:11], v[10:11], 0, s[56:57]
	v_lshl_add_u64 v[14:15], s[22:23], 0, v[130:131]
	v_mov_b32_e32 v133, v1
	s_lshl_b32 s0, s10, 7
	s_waitcnt vmcnt(4)
	s_barrier
	global_load_lds_dwordx4 v[10:11], off
	v_lshl_add_u64 v[10:11], v[12:13], 0, s[56:57]
	s_add_i32 m0, s19, 0x1a000
	s_add_i32 s76, s19, 0x8000
	s_add_i32 s77, s19, 0xa000
	v_lshl_add_u64 v[16:17], s[22:23], 0, v[132:133]
	v_bitop3_b32 v143, v9, s0, v6 bitop3:0xde
	global_load_lds_dwordx4 v[10:11], off
	v_lshl_add_u64 v[10:11], v[14:15], 0, s[56:57]
	s_mov_b32 m0, s76
	s_add_u32 s0, s34, 0x40080
	global_load_lds_dwordx4 v[10:11], off
	v_lshl_add_u64 v[10:11], v[16:17], 0, s[56:57]
	s_mov_b32 m0, s77
	s_addc_u32 s1, s35, 0
	global_load_lds_dwordx4 v[10:11], off
	s_add_i32 m0, s19, 0x1c000
	v_lshl_add_u64 v[10:11], s[0:1], 0, v[0:1]
	global_load_lds_dwordx4 v[10:11], off
	v_lshl_add_u64 v[10:11], s[0:1], 0, v[134:135]
	s_add_i32 m0, s19, 0x1e000
	v_lshlrev_b32_e32 v6, 14, v2
	global_load_lds_dwordx4 v[10:11], off
	v_and_b32_e32 v6, 0xffff8000, v6
	v_lshl_add_u32 v3, v3, 11, v6
	v_and_b32_e32 v2, 1, v2
	v_lshl_or_b32 v2, v2, 6, v3
	v_lshl_add_u32 v136, v4, 1, v2
	v_lshlrev_b32_e32 v2, 14, v5
	v_and_b32_e32 v2, 0xffff8000, v2
	s_waitcnt vmcnt(6)
	v_readlane_b32 s36, v252, 0
	v_lshl_add_u32 v2, v7, 11, v2
	v_and_b32_e32 v3, 1, v5
	v_readlane_b32 s37, v252, 1
	v_lshl_or_b32 v2, v3, 6, v2
	s_mov_b32 s7, s37
	v_or_b32_e32 v144, s10, v18
	v_mov_b32_e32 v137, v1
	v_lshl_add_u32 v138, v8, 1, v2
	v_mov_b32_e32 v139, v1
	s_mov_b32 s78, 0
	v_add_u32_e32 v145, 0, v19
	s_barrier
	v_readlane_b32 s38, v252, 2
	v_readlane_b32 s39, v252, 3
	v_readlane_b32 s40, v252, 4
	v_readlane_b32 s41, v252, 5
	v_readlane_b32 s42, v252, 6
	v_readlane_b32 s43, v252, 7
	v_readlane_b32 s44, v252, 8
	v_readlane_b32 s45, v252, 9
	v_readlane_b32 s46, v252, 10
	v_readlane_b32 s47, v252, 11
	v_readlane_b32 s48, v252, 12
	v_readlane_b32 s49, v252, 13
	v_readlane_b32 s50, v252, 14
	v_readlane_b32 s51, v252, 15
	s_bitcmp1_b32 s54, 0
	s_cbranch_scc0 .Lstg_p9
	s_sleep 127
.Lstg_p9:
.LBB0_1202:
	v_readlane_b32 s36, v252, 18
	s_add_i32 s78, s78, 1
	v_readlane_b32 s42, v252, 24
	s_mul_i32 s0, s78, s55
	s_mul_hi_u32 s1, s78, s42
	s_add_i32 s1, s1, s0
	s_mul_i32 s0, s78, s42
	s_add_u32 s14, s0, s54
	s_addc_u32 s15, s1, s59
	v_mov_b64_e32 v[2:3], s[6:7]
	v_cmp_ge_i64_e64 s[0:1], s[14:15], v[2:3]
	s_and_b64 vcc, exec, s[0:1]
	v_readlane_b32 s37, v252, 19
	v_readlane_b32 s38, v252, 20
	v_readlane_b32 s39, v252, 21
	v_readlane_b32 s40, v252, 22
	v_readlane_b32 s41, v252, 23
	v_readlane_b32 s43, v252, 25
	s_cbranch_vccnz .LBB0_1205
	s_ashr_i32 s10, s14, 31
	s_lshr_b32 s10, s10, 29
	s_add_i32 s10, s14, s10
	s_ashr_i32 s11, s10, 3
	s_and_b32 s10, s10, -8
	s_sub_i32 s10, s14, s10
	s_lshr_b32 s12, s10, 31
	s_or_b32 s12, s25, s12
	s_mul_i32 s10, s12, s10
	s_add_i32 s10, s10, s11
	s_mul_hi_i32 s11, s10, 0x2e8ba2e9
	s_lshr_b32 s12, s11, 31
	s_ashr_i32 s11, s11, 5
	s_add_i32 s11, s11, s12
	s_lshl_b32 s12, s11, 3
	v_readlane_b32 s13, v255, 16
	s_sub_i32 s13, s13, s12
	s_min_i32 s13, s13, 8
	s_abs_i32 s16, s13
	v_cvt_f32_u32_e32 v2, s16
	s_sub_i32 s28, 0, s16
	s_mulk_i32 s11, 0xb0
	s_sub_i32 s11, s10, s11
	v_rcp_iflag_f32_e32 v2, v2
	s_abs_i32 s10, s11
	s_xor_b32 s17, s11, s13
	s_ashr_i32 s17, s17, 31
	v_mul_f32_e32 v2, 0x4f7ffffe, v2
	v_cvt_u32_f32_e32 v2, v2
	s_nop 0
	v_readfirstlane_b32 s29, v2
	s_mul_i32 s28, s28, s29
	s_mul_hi_u32 s28, s29, s28
	s_add_i32 s29, s29, s28
	s_mul_hi_u32 s28, s10, s29
	s_mul_i32 s29, s28, s16
	s_sub_i32 s10, s10, s29
	s_add_i32 s79, s28, 1
	s_sub_i32 s29, s10, s16
	s_cmp_ge_u32 s10, s16
	s_cselect_b32 s28, s79, s28
	s_cselect_b32 s10, s29, s10
	s_add_i32 s29, s28, 1
	s_cmp_ge_u32 s10, s16
	s_cselect_b32 s10, s29, s28
	s_xor_b32 s10, s10, s17
	s_sub_i32 s10, s10, s17
	s_mul_i32 s13, s10, s13
	s_sub_i32 s11, s11, s13
	s_and_b64 vcc, exec, s[4:5]
	s_add_i32 s12, s11, s12
	s_cbranch_vccnz .LBB0_1205
	s_ashr_i32 s12, s12, 3
	s_mul_i32 s12, s12, 9
	s_and_b32 s11, s11, 7
	s_add_i32 s11, s11, s12
	s_add_i32 s12, s11, 1

.LBB0_1268:
	s_add_u32 s35, s74, 0x5000
	v_lshrrev_b32_e32 v20, 1, v10
	s_addc_u32 s61, s75, 0
	v_and_b32_e32 v20, 24, v20
	s_lshl_b32 s0, s0, 5
	v_and_b32_e32 v19, 15, v10
	v_lshlrev_b32_e32 v21, 1, v20
	v_lshlrev_b32_e32 v10, 2, v10
	s_and_b32 s6, s0, 0x60
	s_add_i32 m0, s25, 0x18000
	v_lshl_add_u64 v[8:9], v[8:9], 0, s[56:57]
	v_lshl_or_b32 v190, s1, 6, v19
	v_lshl_or_b32 v19, v19, 6, v21
	s_lshl_b32 s1, s1, 13
	v_and_b32_e32 v10, 32, v10
	s_lshl_b32 s0, s6, 7
	s_waitcnt vmcnt(4)
	s_barrier
	global_load_lds_dwordx4 v[8:9], off
	v_lshl_add_u64 v[6:7], v[6:7], 0, s[56:57]
	s_add_i32 m0, s25, 0x1a000
	s_add_i32 s62, s25, 0x8000
	s_add_i32 s63, s25, 0xa000
	v_bitop3_b32 v191, v19, s0, v10 bitop3:0xde
	global_load_lds_dwordx4 v[6:7], off
	v_lshl_add_u64 v[4:5], v[4:5], 0, s[56:57]
	s_mov_b32 m0, s62
	s_add_u32 s0, s16, 0xb0080
	v_bitop3_b32 v21, v19, s1, v10 bitop3:0xde
	global_load_lds_dwordx4 v[4:5], off
	v_lshl_add_u64 v[2:3], v[2:3], 0, s[56:57]
	s_mov_b32 m0, s63
	s_addc_u32 s1, s17, 0
	global_load_lds_dwordx4 v[2:3], off
	s_add_i32 m0, s25, 0x1c000
	v_lshl_add_u64 v[2:3], s[0:1], 0, v[0:1]
	global_load_lds_dwordx4 v[2:3], off
	v_lshl_add_u64 v[2:3], s[0:1], 0, v[170:171]
	s_add_i32 m0, s25, 0x1e000
	v_or_b32_e32 v192, s6, v20
	global_load_lds_dwordx4 v[2:3], off
	s_movk_i32 s6, 0xb00
	v_lshrrev_b32_e32 v3, 1, v11
	v_mul_lo_u32 v2, v13, s6
	s_mov_b32 s7, 0xb000
	v_mad_u64_u32 v[2:3], s[0:1], v3, s7, v[2:3]
	v_or_b32_e32 v2, v2, v12
	v_add_lshl_u32 v2, v2, v14, 1
	v_mov_b32_e32 v3, v1
	s_mov_b64 s[8:9], 0xb0080
	v_lshl_add_u64 v[172:173], v[2:3], 0, s[8:9]
	v_lshrrev_b32_e32 v3, 1, v15
	v_mul_lo_u32 v2, v17, s6
	v_mad_u64_u32 v[2:3], s[0:1], v3, s7, v[2:3]
	s_waitcnt vmcnt(6)
	v_or_b32_e32 v2, v2, v16
	v_add_lshl_u32 v2, v2, v18, 1
	v_mov_b32_e32 v3, v1
	v_lshl_add_u64 v[174:175], v[2:3], 0, s[8:9]
	s_mov_b32 s64, 0
	v_add_u32_e32 v193, 0, v21
	s_barrier
	s_bitcmp1_b32 s54, 0
	s_cbranch_scc0 .Lstg_p10
	s_sleep 127
	s_sleep 127
.Lstg_p10:
	s_branch .LBB0_1270
.LBB0_1269:
	s_ashr_i32 s13, s12, 31
	s_lshl_b64 s[12:13], s[12:13], 19
	s_lshl_b64 s[10:11], s[10:11], 2
	v_mov_b32_e32 v148, v1
	v_lshl_or_b32 v122, s76, 8, v192
	s_add_u32 s10, s35, s10
	s_addc_u32 s11, s61, s11
	v_add_u32_e32 v146, v122, v148
	v_ashrrev_i32_e32 v147, 31, v146
	v_lshl_add_u64 v[126:127], v[146:147], 2, s[10:11]
	s_add_u32 s10, s88, s12
	v_add_u32_e32 v148, v148, v190
	s_addc_u32 s11, s89, s13
	v_ashrrev_i32_e32 v149, 31, v148
	v_lshl_add_u64 v[146:147], v[146:147], 1, s[10:11]
	v_lshlrev_b64 v[148:149], 11, v[148:149]
	v_lshl_add_u64 v[176:177], v[146:147], 0, v[148:149]
	global_load_dwordx4 v[130:133], v[126:127], off offset:16
	global_load_dwordx4 v[134:137], v[126:127], off
	global_load_dwordx4 v[122:125], v[126:127], off offset:528
	s_nop 0
	global_load_dwordx4 v[126:129], v[126:127], off offset:512
	s_nop 0
	global_load_dwordx4 v[194:197], v[176:177], off
	global_load_dwordx4 v[198:201], v[176:177], off offset:256
	v_add_co_u32_e32 v188, vcc, s53, v176
	v_lshl_add_u64 v[184:185], v[176:177], 0, s[68:69]
	s_nop 0
	v_addc_co_u32_e32 v189, vcc, 0, v177, vcc
	global_load_dwordx4 v[202:205], v[188:189], off
	global_load_dwordx4 v[162:165], v[184:185], off offset:256
	s_mov_b32 s10, 0x10000
	v_add_co_u32_e32 v186, vcc, s10, v176
	v_lshl_add_u64 v[182:183], v[176:177], 0, s[70:71]
	s_nop 0
	v_addc_co_u32_e32 v187, vcc, 0, v177, vcc
	global_load_dwordx4 v[158:161], v[186:187], off
	global_load_dwordx4 v[154:157], v[182:183], off offset:256
	v_add_co_u32_e32 v180, vcc, s52, v176
	v_lshl_add_u64 v[178:179], v[176:177], 0, s[72:73]
	s_nop 0
	v_addc_co_u32_e32 v181, vcc, 0, v177, vcc
	global_load_dwordx4 v[150:153], v[180:181], off
	global_load_dwordx4 v[146:149], v[178:179], off offset:256
	s_mov_b32 s10, 0x40000
	s_mov_b32 s76, s65
	s_mov_b32 s12, s74
	s_mov_b64 s[16:17], s[8:9]
	s_mov_b64 s[14:15], s[6:7]
	s_waitcnt vmcnt(0)
	v_lshlrev_b32_e32 v206, 16, v194
	v_and_b32_e32 v207, 0xffff0000, v194
	v_lshlrev_b32_e32 v194, 16, v195
	v_and_b32_e32 v195, 0xffff0000, v195
	v_lshlrev_b32_e32 v208, 16, v196
	v_and_b32_e32 v209, 0xffff0000, v196
	v_lshlrev_b32_e32 v196, 16, v197
	v_and_b32_e32 v197, 0xffff0000, v197
	v_pk_fma_f32 v[144:145], v[144:145], v[136:137], v[194:195]
	v_pk_fma_f32 v[142:143], v[142:143], v[134:135], v[206:207]
	v_pk_fma_f32 v[194:195], v[140:141], v[132:133], v[196:197]
	v_pk_fma_f32 v[140:141], v[138:139], v[130:131], v[208:209]
	v_cvt_pk_bf16_f32 v138, v142, v143
	v_cvt_pk_bf16_f32 v139, v144, v145
	v_lshlrev_b32_e32 v142, 16, v200
	v_cvt_pk_bf16_f32 v140, v140, v141
	v_cvt_pk_bf16_f32 v141, v194, v195
	global_store_dwordx4 v[176:177], v[138:141], off
	v_and_b32_e32 v143, 0xffff0000, v200
	v_lshlrev_b32_e32 v144, 16, v201
	v_lshlrev_b32_e32 v138, 16, v198
	v_and_b32_e32 v139, 0xffff0000, v198
	v_and_b32_e32 v145, 0xffff0000, v201
	v_lshlrev_b32_e32 v140, 16, v199
	v_and_b32_e32 v141, 0xffff0000, v199
	v_pk_fma_f32 v[118:119], v[118:119], v[126:127], v[138:139]
	v_pk_fma_f32 v[138:139], v[116:117], v[124:125], v[144:145]
	v_pk_fma_f32 v[116:117], v[114:115], v[122:123], v[142:143]
	v_pk_fma_f32 v[120:121], v[120:121], v[128:129], v[140:141]
	v_cvt_pk_bf16_f32 v114, v118, v119
	v_lshlrev_b32_e32 v118, 16, v204
	v_cvt_pk_bf16_f32 v115, v120, v121
	v_cvt_pk_bf16_f32 v116, v116, v117
	v_cvt_pk_bf16_f32 v117, v138, v139
	global_store_dwordx4 v[176:177], v[114:117], off offset:256
	v_and_b32_e32 v119, 0xffff0000, v204
	v_lshlrev_b32_e32 v120, 16, v205
	v_lshlrev_b32_e32 v114, 16, v202
	v_and_b32_e32 v115, 0xffff0000, v202
	v_lshlrev_b32_e32 v116, 16, v203
	v_and_b32_e32 v117, 0xffff0000, v203
	v_and_b32_e32 v121, 0xffff0000, v205
	v_pk_fma_f32 v[112:113], v[112:113], v[136:137], v[116:117]
	v_pk_fma_f32 v[110:111], v[110:111], v[134:135], v[114:115]
	v_pk_fma_f32 v[114:115], v[108:109], v[132:133], v[120:121]
	v_pk_fma_f32 v[108:109], v[106:107], v[130:131], v[118:119]
	v_cvt_pk_bf16_f32 v106, v110, v111
	v_cvt_pk_bf16_f32 v107, v112, v113
	v_lshlrev_b32_e32 v110, 16, v164
	v_cvt_pk_bf16_f32 v108, v108, v109
	v_cvt_pk_bf16_f32 v109, v114, v115
	global_store_dwordx4 v[188:189], v[106:109], off
	v_and_b32_e32 v111, 0xffff0000, v164
	v_lshlrev_b32_e32 v112, 16, v165
	v_lshlrev_b32_e32 v106, 16, v162
	v_and_b32_e32 v107, 0xffff0000, v162
	v_and_b32_e32 v113, 0xffff0000, v165
	v_lshlrev_b32_e32 v108, 16, v163
	v_and_b32_e32 v109, 0xffff0000, v163
	v_pk_fma_f32 v[102:103], v[102:103], v[126:127], v[106:107]
	v_pk_fma_f32 v[106:107], v[100:101], v[124:125], v[112:113]
	v_pk_fma_f32 v[100:101], v[98:99], v[122:123], v[110:111]
	v_pk_fma_f32 v[104:105], v[104:105], v[128:129], v[108:109]
	v_cvt_pk_bf16_f32 v98, v102, v103
	v_lshlrev_b32_e32 v102, 16, v160
	v_cvt_pk_bf16_f32 v99, v104, v105
	v_cvt_pk_bf16_f32 v100, v100, v101
	v_cvt_pk_bf16_f32 v101, v106, v107
	global_store_dwordx4 v[184:185], v[98:101], off offset:256
	v_and_b32_e32 v103, 0xffff0000, v160
	v_lshlrev_b32_e32 v104, 16, v161
	v_lshlrev_b32_e32 v98, 16, v158
	v_and_b32_e32 v99, 0xffff0000, v158
	v_lshlrev_b32_e32 v100, 16, v159
	v_and_b32_e32 v101, 0xffff0000, v159
	v_and_b32_e32 v105, 0xffff0000, v161
	v_pk_fma_f32 v[96:97], v[96:97], v[136:137], v[100:101]
	v_pk_fma_f32 v[94:95], v[94:95], v[134:135], v[98:99]
	v_pk_fma_f32 v[98:99], v[92:93], v[132:133], v[104:105]
	v_pk_fma_f32 v[92:93], v[90:91], v[130:131], v[102:103]
	v_cvt_pk_bf16_f32 v90, v94, v95
	v_cvt_pk_bf16_f32 v91, v96, v97
	v_lshlrev_b32_e32 v94, 16, v156
	v_cvt_pk_bf16_f32 v92, v92, v93
	v_cvt_pk_bf16_f32 v93, v98, v99
	global_store_dwordx4 v[186:187], v[90:93], off
	v_and_b32_e32 v95, 0xffff0000, v156
	v_lshlrev_b32_e32 v96, 16, v157
	v_lshlrev_b32_e32 v90, 16, v154
	v_and_b32_e32 v91, 0xffff0000, v154
	v_and_b32_e32 v97, 0xffff0000, v157
	v_lshlrev_b32_e32 v92, 16, v155
	v_and_b32_e32 v93, 0xffff0000, v155
	v_pk_fma_f32 v[86:87], v[86:87], v[126:127], v[90:91]
	v_pk_fma_f32 v[90:91], v[84:85], v[124:125], v[96:97]
	v_pk_fma_f32 v[84:85], v[82:83], v[122:123], v[94:95]
	v_pk_fma_f32 v[88:89], v[88:89], v[128:129], v[92:93]
	v_cvt_pk_bf16_f32 v82, v86, v87
	v_lshlrev_b32_e32 v86, 16, v152
	v_cvt_pk_bf16_f32 v83, v88, v89
	v_cvt_pk_bf16_f32 v84, v84, v85
	v_cvt_pk_bf16_f32 v85, v90, v91
	global_store_dwordx4 v[182:183], v[82:85], off offset:256
	v_and_b32_e32 v87, 0xffff0000, v152
	v_lshlrev_b32_e32 v88, 16, v153
	v_lshlrev_b32_e32 v82, 16, v150
	v_and_b32_e32 v83, 0xffff0000, v150
	v_lshlrev_b32_e32 v84, 16, v151
	v_and_b32_e32 v85, 0xffff0000, v151
	v_and_b32_e32 v89, 0xffff0000, v153
	v_pk_fma_f32 v[80:81], v[80:81], v[136:137], v[84:85]
	v_pk_fma_f32 v[78:79], v[78:79], v[134:135], v[82:83]
	v_pk_fma_f32 v[82:83], v[76:77], v[132:133], v[88:89]
	v_pk_fma_f32 v[76:77], v[74:75], v[130:131], v[86:87]
	v_cvt_pk_bf16_f32 v74, v78, v79
	v_cvt_pk_bf16_f32 v75, v80, v81
	v_lshlrev_b32_e32 v78, 16, v148
	v_cvt_pk_bf16_f32 v76, v76, v77
	v_cvt_pk_bf16_f32 v77, v82, v83
	global_store_dwordx4 v[180:181], v[74:77], off
	v_and_b32_e32 v79, 0xffff0000, v148
	v_lshlrev_b32_e32 v80, 16, v149
	v_lshlrev_b32_e32 v74, 16, v146
	v_and_b32_e32 v75, 0xffff0000, v146
	v_and_b32_e32 v81, 0xffff0000, v149
	v_lshlrev_b32_e32 v76, 16, v147
	v_and_b32_e32 v77, 0xffff0000, v147
	v_pk_fma_f32 v[70:71], v[70:71], v[126:127], v[74:75]
	v_pk_fma_f32 v[74:75], v[68:69], v[124:125], v[80:81]
	v_pk_fma_f32 v[68:69], v[66:67], v[122:123], v[78:79]
	v_pk_fma_f32 v[72:73], v[72:73], v[128:129], v[76:77]
	v_cvt_pk_bf16_f32 v66, v70, v71
	v_add_co_u32_e32 v106, vcc, s10, v176
	v_cvt_pk_bf16_f32 v67, v72, v73
	v_cvt_pk_bf16_f32 v68, v68, v69
	v_cvt_pk_bf16_f32 v69, v74, v75
	global_store_dwordx4 v[178:179], v[66:69], off offset:256
	s_nop 0
	v_addc_co_u32_e32 v107, vcc, 0, v177, vcc
	v_lshl_add_u64 v[104:105], v[176:177], 0, s[2:3]
	global_load_dwordx4 v[80:83], v[106:107], off
	global_load_dwordx4 v[84:87], v[104:105], off offset:256
	v_add_co_u32_e32 v110, vcc, s54, v176
	s_mov_b64 s[10:11], 0x48000
	s_nop 0
	v_addc_co_u32_e32 v111, vcc, 0, v177, vcc
	v_lshl_add_u64 v[108:109], v[176:177], 0, s[10:11]
	global_load_dwordx4 v[88:91], v[110:111], off
	global_load_dwordx4 v[92:95], v[108:109], off offset:256
	s_mov_b64 s[10:11], 0x50000
	v_lshl_add_u64 v[78:79], v[176:177], 0, s[10:11]
	s_mov_b32 s10, 0x50000
	v_add_co_u32_e32 v112, vcc, s10, v176
	s_mov_b64 s[10:11], 0x58000
	s_nop 0
	v_addc_co_u32_e32 v113, vcc, 0, v177, vcc
	global_load_dwordx4 v[96:99], v[112:113], off
	global_load_dwordx4 v[100:103], v[78:79], off offset:256
	v_add_co_u32_e32 v76, vcc, s66, v176
	v_lshl_add_u64 v[74:75], v[176:177], 0, s[10:11]
	s_nop 0
	v_addc_co_u32_e32 v77, vcc, 0, v177, vcc
	global_load_dwordx4 v[70:73], v[76:77], off
	global_load_dwordx4 v[66:69], v[74:75], off offset:256
	s_and_b64 vcc, exec, s[0:1]
	s_waitcnt vmcnt(0)
	v_lshlrev_b32_e32 v114, 16, v80
	v_and_b32_e32 v115, 0xffff0000, v80
	v_lshlrev_b32_e32 v80, 16, v81
	v_and_b32_e32 v81, 0xffff0000, v81
	v_lshlrev_b32_e32 v116, 16, v82
	v_and_b32_e32 v117, 0xffff0000, v82
	v_lshlrev_b32_e32 v82, 16, v83
	v_and_b32_e32 v83, 0xffff0000, v83
	v_pk_fma_f32 v[64:65], v[64:65], v[136:137], v[80:81]
	v_pk_fma_f32 v[62:63], v[62:63], v[134:135], v[114:115]
	v_pk_fma_f32 v[80:81], v[60:61], v[132:133], v[82:83]
	v_pk_fma_f32 v[60:61], v[58:59], v[130:131], v[116:117]
	v_cvt_pk_bf16_f32 v58, v62, v63
	v_cvt_pk_bf16_f32 v59, v64, v65
	v_lshlrev_b32_e32 v62, 16, v86
	v_cvt_pk_bf16_f32 v60, v60, v61
	v_cvt_pk_bf16_f32 v61, v80, v81
	global_store_dwordx4 v[106:107], v[58:61], off
	v_and_b32_e32 v63, 0xffff0000, v86
	v_lshlrev_b32_e32 v64, 16, v87
	v_lshlrev_b32_e32 v58, 16, v84
	v_and_b32_e32 v59, 0xffff0000, v84
	v_and_b32_e32 v65, 0xffff0000, v87
	v_lshlrev_b32_e32 v60, 16, v85
	v_and_b32_e32 v61, 0xffff0000, v85
	v_pk_fma_f32 v[54:55], v[54:55], v[126:127], v[58:59]
	v_pk_fma_f32 v[58:59], v[52:53], v[124:125], v[64:65]
	v_pk_fma_f32 v[52:53], v[50:51], v[122:123], v[62:63]
	v_pk_fma_f32 v[56:57], v[56:57], v[128:129], v[60:61]
	v_cvt_pk_bf16_f32 v50, v54, v55
	v_lshlrev_b32_e32 v54, 16, v90
	v_cvt_pk_bf16_f32 v51, v56, v57
	v_cvt_pk_bf16_f32 v52, v52, v53
	v_cvt_pk_bf16_f32 v53, v58, v59
	global_store_dwordx4 v[104:105], v[50:53], off offset:256
	v_and_b32_e32 v55, 0xffff0000, v90
	v_lshlrev_b32_e32 v56, 16, v91
	v_lshlrev_b32_e32 v50, 16, v88
	v_and_b32_e32 v51, 0xffff0000, v88
	v_lshlrev_b32_e32 v52, 16, v89
	v_and_b32_e32 v53, 0xffff0000, v89
	v_and_b32_e32 v57, 0xffff0000, v91
	v_pk_fma_f32 v[48:49], v[48:49], v[136:137], v[52:53]
	v_pk_fma_f32 v[46:47], v[46:47], v[134:135], v[50:51]
	v_pk_fma_f32 v[50:51], v[44:45], v[132:133], v[56:57]
	v_pk_fma_f32 v[44:45], v[42:43], v[130:131], v[54:55]
	v_cvt_pk_bf16_f32 v42, v46, v47
	v_cvt_pk_bf16_f32 v43, v48, v49
	v_lshlrev_b32_e32 v46, 16, v94
	v_cvt_pk_bf16_f32 v44, v44, v45
	v_cvt_pk_bf16_f32 v45, v50, v51
	global_store_dwordx4 v[110:111], v[42:45], off
	v_and_b32_e32 v47, 0xffff0000, v94
	v_lshlrev_b32_e32 v48, 16, v95
	v_lshlrev_b32_e32 v42, 16, v92
	v_and_b32_e32 v43, 0xffff0000, v92
	v_and_b32_e32 v49, 0xffff0000, v95
	v_lshlrev_b32_e32 v44, 16, v93
	v_and_b32_e32 v45, 0xffff0000, v93
	v_pk_fma_f32 v[38:39], v[38:39], v[126:127], v[42:43]
	v_pk_fma_f32 v[42:43], v[36:37], v[124:125], v[48:49]
	v_pk_fma_f32 v[36:37], v[34:35], v[122:123], v[46:47]
	v_pk_fma_f32 v[40:41], v[40:41], v[128:129], v[44:45]
	v_cvt_pk_bf16_f32 v34, v38, v39
	v_lshlrev_b32_e32 v38, 16, v98
	v_cvt_pk_bf16_f32 v35, v40, v41
	v_cvt_pk_bf16_f32 v36, v36, v37
	v_cvt_pk_bf16_f32 v37, v42, v43
	global_store_dwordx4 v[108:109], v[34:37], off offset:256
	v_and_b32_e32 v39, 0xffff0000, v98
	v_lshlrev_b32_e32 v40, 16, v99
	v_lshlrev_b32_e32 v34, 16, v96
	v_and_b32_e32 v35, 0xffff0000, v96
	v_lshlrev_b32_e32 v36, 16, v97
	v_and_b32_e32 v37, 0xffff0000, v97
	v_and_b32_e32 v41, 0xffff0000, v99
	v_pk_fma_f32 v[32:33], v[32:33], v[136:137], v[36:37]
	v_pk_fma_f32 v[30:31], v[30:31], v[134:135], v[34:35]
	v_pk_fma_f32 v[34:35], v[28:29], v[132:133], v[40:41]
	v_pk_fma_f32 v[28:29], v[26:27], v[130:131], v[38:39]
	v_cvt_pk_bf16_f32 v26, v30, v31
	v_cvt_pk_bf16_f32 v27, v32, v33
	v_lshlrev_b32_e32 v30, 16, v102
	v_cvt_pk_bf16_f32 v28, v28, v29
	v_cvt_pk_bf16_f32 v29, v34, v35
	global_store_dwordx4 v[112:113], v[26:29], off
	v_and_b32_e32 v31, 0xffff0000, v102
	v_lshlrev_b32_e32 v32, 16, v103
	v_lshlrev_b32_e32 v26, 16, v100
	v_and_b32_e32 v27, 0xffff0000, v100
	v_and_b32_e32 v33, 0xffff0000, v103
	v_lshlrev_b32_e32 v28, 16, v101
	v_and_b32_e32 v29, 0xffff0000, v101
	v_pk_fma_f32 v[22:23], v[22:23], v[126:127], v[26:27]
	v_pk_fma_f32 v[26:27], v[20:21], v[124:125], v[32:33]
	v_pk_fma_f32 v[20:21], v[18:19], v[122:123], v[30:31]
	v_pk_fma_f32 v[24:25], v[24:25], v[128:129], v[28:29]
	v_cvt_pk_bf16_f32 v18, v22, v23
	v_lshlrev_b32_e32 v22, 16, v72
	v_cvt_pk_bf16_f32 v19, v24, v25
	v_cvt_pk_bf16_f32 v20, v20, v21
	v_cvt_pk_bf16_f32 v21, v26, v27
	global_store_dwordx4 v[78:79], v[18:21], off offset:256
	v_and_b32_e32 v23, 0xffff0000, v72
	v_lshlrev_b32_e32 v24, 16, v73
	v_lshlrev_b32_e32 v18, 16, v70
	v_and_b32_e32 v19, 0xffff0000, v70
	v_lshlrev_b32_e32 v20, 16, v71
	v_and_b32_e32 v21, 0xffff0000, v71
	v_and_b32_e32 v25, 0xffff0000, v73
	v_pk_fma_f32 v[16:17], v[16:17], v[136:137], v[20:21]
	v_pk_fma_f32 v[14:15], v[14:15], v[134:135], v[18:19]
	v_pk_fma_f32 v[18:19], v[12:13], v[132:133], v[24:25]
	v_pk_fma_f32 v[12:13], v[10:11], v[130:131], v[22:23]
	v_cvt_pk_bf16_f32 v10, v14, v15
	v_cvt_pk_bf16_f32 v11, v16, v17
	v_lshlrev_b32_e32 v14, 16, v68
	v_cvt_pk_bf16_f32 v12, v12, v13
	v_cvt_pk_bf16_f32 v13, v18, v19
	global_store_dwordx4 v[76:77], v[10:13], off
	v_and_b32_e32 v15, 0xffff0000, v68
	v_lshlrev_b32_e32 v16, 16, v69
	v_lshlrev_b32_e32 v10, 16, v66
	v_and_b32_e32 v11, 0xffff0000, v66
	v_and_b32_e32 v17, 0xffff0000, v69
	v_lshlrev_b32_e32 v12, 16, v67
	v_and_b32_e32 v13, 0xffff0000, v67
	v_pk_fma_f32 v[6:7], v[6:7], v[126:127], v[10:11]
	v_pk_fma_f32 v[10:11], v[4:5], v[124:125], v[16:17]
	v_pk_fma_f32 v[4:5], v[2:3], v[122:123], v[14:15]
	v_pk_fma_f32 v[8:9], v[8:9], v[128:129], v[12:13]
	v_cvt_pk_bf16_f32 v2, v6, v7
	s_nop 0
	v_cvt_pk_bf16_f32 v3, v8, v9
	v_cvt_pk_bf16_f32 v4, v4, v5
	v_cvt_pk_bf16_f32 v5, v10, v11
	global_store_dwordx4 v[74:75], v[2:5], off offset:256
	s_cbranch_vccnz .LBB0_1281
